# PV ring 9 slots / 8 pairs in flight, refill after every MFMA, one lgkmcnt wait per two MFMAs at unchanged latency tolerance (16 waits instead of 32 per tile)
# speedup vs baseline: 1.0033x; 1.0033x over previous
.LBB0_517:
	v_fmamk_f32 v144, v144, 0x3e0293ee, v237
	v_fmamk_f32 v145, v145, 0x3e0293ee, v237
	v_fmamk_f32 v146, v146, 0x3e0293ee, v237
	v_fmamk_f32 v147, v147, 0x3e0293ee, v237
	v_fmamk_f32 v148, v148, 0x3e0293ee, v237
	v_fmamk_f32 v149, v149, 0x3e0293ee, v237
	v_fmamk_f32 v150, v150, 0x3e0293ee, v237
	v_fmamk_f32 v151, v151, 0x3e0293ee, v237
	v_fmamk_f32 v152, v152, 0x3e0293ee, v237
	v_fmamk_f32 v153, v153, 0x3e0293ee, v237
	v_fmamk_f32 v154, v154, 0x3e0293ee, v237
	v_fmamk_f32 v155, v155, 0x3e0293ee, v237
	v_fmamk_f32 v156, v156, 0x3e0293ee, v237
	v_fmamk_f32 v157, v157, 0x3e0293ee, v237
	v_fmamk_f32 v158, v158, 0x3e0293ee, v237
	v_fmamk_f32 v159, v159, 0x3e0293ee, v237
	v_fmamk_f32 v128, v128, 0x3e0293ee, v237
	v_fmamk_f32 v129, v129, 0x3e0293ee, v237
	v_fmamk_f32 v130, v130, 0x3e0293ee, v237
	v_fmamk_f32 v131, v131, 0x3e0293ee, v237
	v_fmamk_f32 v132, v132, 0x3e0293ee, v237
	v_fmamk_f32 v133, v133, 0x3e0293ee, v237
	v_fmamk_f32 v134, v134, 0x3e0293ee, v237
	v_fmamk_f32 v135, v135, 0x3e0293ee, v237
	v_fmamk_f32 v136, v136, 0x3e0293ee, v237
	v_fmamk_f32 v137, v137, 0x3e0293ee, v237
	v_fmamk_f32 v138, v138, 0x3e0293ee, v237
	v_fmamk_f32 v139, v139, 0x3e0293ee, v237
	v_fmamk_f32 v140, v140, 0x3e0293ee, v237
	v_fmamk_f32 v141, v141, 0x3e0293ee, v237
	v_fmamk_f32 v142, v142, 0x3e0293ee, v237
	v_fmamk_f32 v192, v143, 0x3e0293ee, v237
	v_exp_f32_e32 v143, v144
	v_exp_f32_e32 v145, v145
	v_exp_f32_e32 v146, v146
	v_exp_f32_e32 v147, v147
	v_exp_f32_e32 v148, v148
	v_exp_f32_e32 v193, v128
	v_exp_f32_e32 v149, v149
	v_add_f32_e32 v128, v145, v143
	v_exp_f32_e32 v150, v150
	v_add_f32_e32 v128, v146, v128
	v_exp_f32_e32 v151, v151
	v_add_f32_e32 v128, v147, v128
	v_exp_f32_e32 v152, v152
	v_add_f32_e32 v128, v148, v128
	v_exp_f32_e32 v153, v153
	v_add_f32_e32 v128, v149, v128
	v_exp_f32_e32 v154, v154
	v_add_f32_e32 v128, v150, v128
	v_exp_f32_e32 v155, v155
	v_add_f32_e32 v128, v151, v128
	v_exp_f32_e32 v156, v156
	v_add_f32_e32 v128, v152, v128
	v_exp_f32_e32 v157, v157
	v_add_f32_e32 v128, v153, v128
	v_exp_f32_e32 v158, v158
	v_add_f32_e32 v128, v154, v128
	v_exp_f32_e32 v159, v159
	v_add_f32_e32 v128, v155, v128
	v_add_f32_e32 v128, v156, v128
	v_exp_f32_e32 v194, v129
	v_add_f32_e32 v128, v157, v128
	v_exp_f32_e32 v195, v130
	v_add_f32_e32 v128, v158, v128
	v_exp_f32_e32 v196, v131
	v_add_f32_e32 v128, v159, v128
	v_exp_f32_e32 v197, v132
	v_add_f32_e32 v128, v193, v128
	v_exp_f32_e32 v198, v133
	v_add_f32_e32 v128, v194, v128
	v_exp_f32_e32 v199, v134
	v_add_f32_e32 v128, v195, v128
	v_exp_f32_e32 v135, v135
	v_add_f32_e32 v128, v196, v128
	v_exp_f32_e32 v200, v136
	v_add_f32_e32 v128, v197, v128
	v_exp_f32_e32 v201, v137
	v_add_f32_e32 v128, v198, v128
	v_exp_f32_e32 v202, v138
	v_add_f32_e32 v128, v199, v128
	v_exp_f32_e32 v203, v139
	v_add_f32_e32 v128, v135, v128
	v_exp_f32_e32 v204, v140
	v_add_f32_e32 v128, v200, v128
	v_exp_f32_e32 v205, v141
	v_add_f32_e32 v128, v201, v128
	v_exp_f32_e32 v206, v142
	v_add_f32_e32 v128, v202, v128
	v_exp_f32_e32 v192, v192
	v_add_f32_e32 v128, v203, v128
	v_add_f32_e32 v128, v204, v128
	v_add_f32_e32 v128, v205, v128
	v_add_f32_e32 v128, v206, v128
	v_add_f32_e32 v128, v192, v128
	v_add_f32_e32 v144, v232, v128
	v_cvt_pk_bf16_f32 v128, v143, v145
	v_cvt_pk_bf16_f32 v129, v146, v147
	v_cvt_pk_bf16_f32 v130, v148, v149
	v_cvt_pk_bf16_f32 v131, v150, v151
	v_cvt_pk_bf16_f32 v136, v152, v153
	v_cvt_pk_bf16_f32 v137, v154, v155
	v_cvt_pk_bf16_f32 v138, v156, v157
	v_cvt_pk_bf16_f32 v139, v158, v159
	v_cvt_pk_bf16_f32 v132, v193, v194
	v_cvt_pk_bf16_f32 v133, v195, v196
	v_cvt_pk_bf16_f32 v134, v197, v198
	v_cvt_pk_bf16_f32 v135, v199, v135
	v_cvt_pk_bf16_f32 v140, v200, v201
	v_cvt_pk_bf16_f32 v141, v202, v203
	v_cvt_pk_bf16_f32 v142, v204, v205
	v_cvt_pk_bf16_f32 v143, v206, v192
	v_lshl_add_u32 v145, s76, 15, v230
	ds_read_b64_tr_b16 v[146:147], v145 offset:0
	ds_read_b64_tr_b16 v[148:149], v145 offset:4096
	ds_read_b64_tr_b16 v[150:151], v145 offset:512
	ds_read_b64_tr_b16 v[152:153], v145 offset:4608
	ds_read_b64_tr_b16 v[154:155], v145 offset:1024
	ds_read_b64_tr_b16 v[156:157], v145 offset:5120
	ds_read_b64_tr_b16 v[192:193], v145 offset:1536
	ds_read_b64_tr_b16 v[194:195], v145 offset:5632
	ds_read_b64_tr_b16 v[196:197], v145 offset:2048
	ds_read_b64_tr_b16 v[198:199], v145 offset:6144
	ds_read_b64_tr_b16 v[200:201], v145 offset:2560
	ds_read_b64_tr_b16 v[202:203], v145 offset:6656
	ds_read_b64_tr_b16 v[204:205], v145 offset:3072
	ds_read_b64_tr_b16 v[206:207], v145 offset:7168
	ds_read_b64_tr_b16 v[232:233], v145 offset:3584
	ds_read_b64_tr_b16 v[234:235], v145 offset:7680
	s_waitcnt lgkmcnt(12)
	s_nop 0
	v_mfma_f32_32x32x16_bf16 v[0:15], v[128:131], v[146:149], v[0:15]
	ds_read_b64_tr_b16 v[240:241], v145 offset:8192
	ds_read_b64_tr_b16 v[242:243], v145 offset:12288
	v_mfma_f32_32x32x16_bf16 v[112:127], v[128:131], v[150:153], v[112:127]
	ds_read_b64_tr_b16 v[146:147], v145 offset:8704
	ds_read_b64_tr_b16 v[148:149], v145 offset:12800
	s_waitcnt lgkmcnt(12)
	v_mfma_f32_32x32x16_bf16 v[96:111], v[128:131], v[154:157], v[96:111]
	ds_read_b64_tr_b16 v[150:151], v145 offset:9216
	ds_read_b64_tr_b16 v[152:153], v145 offset:13312
	v_mfma_f32_32x32x16_bf16 v[80:95], v[128:131], v[192:195], v[80:95]
	ds_read_b64_tr_b16 v[154:155], v145 offset:9728
	ds_read_b64_tr_b16 v[156:157], v145 offset:13824
	s_waitcnt lgkmcnt(12)
	v_mfma_f32_32x32x16_bf16 v[64:79], v[128:131], v[196:199], v[64:79]
	ds_read_b64_tr_b16 v[192:193], v145 offset:10240
	ds_read_b64_tr_b16 v[194:195], v145 offset:14336
	v_mfma_f32_32x32x16_bf16 v[48:63], v[128:131], v[200:203], v[48:63]
	ds_read_b64_tr_b16 v[196:197], v145 offset:10752
	ds_read_b64_tr_b16 v[198:199], v145 offset:14848
	s_waitcnt lgkmcnt(12)
	v_mfma_f32_32x32x16_bf16 v[32:47], v[128:131], v[204:207], v[32:47]
	ds_read_b64_tr_b16 v[200:201], v145 offset:11264
	ds_read_b64_tr_b16 v[202:203], v145 offset:15360
	v_mfma_f32_32x32x16_bf16 v[16:31], v[128:131], v[232:235], v[16:31]
	ds_read_b64_tr_b16 v[204:205], v145 offset:11776
	ds_read_b64_tr_b16 v[206:207], v145 offset:15872
	s_waitcnt lgkmcnt(12)
	v_mfma_f32_32x32x16_bf16 v[0:15], v[136:139], v[240:243], v[0:15]
	ds_read_b64_tr_b16 v[232:233], v145 offset:16384
	ds_read_b64_tr_b16 v[234:235], v145 offset:20480
	v_mfma_f32_32x32x16_bf16 v[112:127], v[136:139], v[146:149], v[112:127]
	ds_read_b64_tr_b16 v[240:241], v145 offset:16896
	ds_read_b64_tr_b16 v[242:243], v145 offset:20992
	s_waitcnt lgkmcnt(12)
	v_mfma_f32_32x32x16_bf16 v[96:111], v[136:139], v[150:153], v[96:111]
	ds_read_b64_tr_b16 v[146:147], v145 offset:17408
	ds_read_b64_tr_b16 v[148:149], v145 offset:21504
	v_mfma_f32_32x32x16_bf16 v[80:95], v[136:139], v[154:157], v[80:95]
	ds_read_b64_tr_b16 v[150:151], v145 offset:17920
	ds_read_b64_tr_b16 v[152:153], v145 offset:22016
	s_waitcnt lgkmcnt(12)
	v_mfma_f32_32x32x16_bf16 v[64:79], v[136:139], v[192:195], v[64:79]
	ds_read_b64_tr_b16 v[154:155], v145 offset:18432
	ds_read_b64_tr_b16 v[156:157], v145 offset:22528
	v_mfma_f32_32x32x16_bf16 v[48:63], v[136:139], v[196:199], v[48:63]
	ds_read_b64_tr_b16 v[192:193], v145 offset:18944
	ds_read_b64_tr_b16 v[194:195], v145 offset:23040
	s_waitcnt lgkmcnt(12)
	v_mfma_f32_32x32x16_bf16 v[32:47], v[136:139], v[200:203], v[32:47]
	ds_read_b64_tr_b16 v[196:197], v145 offset:19456
	ds_read_b64_tr_b16 v[198:199], v145 offset:23552
	v_mfma_f32_32x32x16_bf16 v[16:31], v[136:139], v[204:207], v[16:31]
	ds_read_b64_tr_b16 v[200:201], v145 offset:19968
	ds_read_b64_tr_b16 v[202:203], v145 offset:24064
	s_waitcnt lgkmcnt(12)
	v_mfma_f32_32x32x16_bf16 v[0:15], v[132:135], v[232:235], v[0:15]
	ds_read_b64_tr_b16 v[204:205], v145 offset:24576
	ds_read_b64_tr_b16 v[206:207], v145 offset:28672
	v_mfma_f32_32x32x16_bf16 v[112:127], v[132:135], v[240:243], v[112:127]
	ds_read_b64_tr_b16 v[232:233], v145 offset:25088
	ds_read_b64_tr_b16 v[234:235], v145 offset:29184
	s_waitcnt lgkmcnt(12)
	v_mfma_f32_32x32x16_bf16 v[96:111], v[132:135], v[146:149], v[96:111]
	ds_read_b64_tr_b16 v[240:241], v145 offset:25600
	ds_read_b64_tr_b16 v[242:243], v145 offset:29696
	v_mfma_f32_32x32x16_bf16 v[80:95], v[132:135], v[150:153], v[80:95]
	ds_read_b64_tr_b16 v[146:147], v145 offset:26112
	ds_read_b64_tr_b16 v[148:149], v145 offset:30208
	s_waitcnt lgkmcnt(12)
	v_mfma_f32_32x32x16_bf16 v[64:79], v[132:135], v[154:157], v[64:79]
	ds_read_b64_tr_b16 v[150:151], v145 offset:26624
	ds_read_b64_tr_b16 v[152:153], v145 offset:30720
	v_mfma_f32_32x32x16_bf16 v[48:63], v[132:135], v[192:195], v[48:63]
	ds_read_b64_tr_b16 v[154:155], v145 offset:27136
	ds_read_b64_tr_b16 v[156:157], v145 offset:31232
	s_waitcnt lgkmcnt(12)
	v_mfma_f32_32x32x16_bf16 v[32:47], v[132:135], v[196:199], v[32:47]
	ds_read_b64_tr_b16 v[192:193], v145 offset:27648
	ds_read_b64_tr_b16 v[194:195], v145 offset:31744
	v_mfma_f32_32x32x16_bf16 v[16:31], v[132:135], v[200:203], v[16:31]
	ds_read_b64_tr_b16 v[196:197], v145 offset:28160
	ds_read_b64_tr_b16 v[198:199], v145 offset:32256
	s_waitcnt lgkmcnt(12)
	v_mfma_f32_32x32x16_bf16 v[0:15], v[140:143], v[204:207], v[0:15]
	v_mfma_f32_32x32x16_bf16 v[112:127], v[140:143], v[232:235], v[112:127]
	s_waitcnt lgkmcnt(8)
	v_mfma_f32_32x32x16_bf16 v[96:111], v[140:143], v[240:243], v[96:111]
	v_mfma_f32_32x32x16_bf16 v[80:95], v[140:143], v[146:149], v[80:95]
	s_waitcnt lgkmcnt(4)
	v_mfma_f32_32x32x16_bf16 v[64:79], v[140:143], v[150:153], v[64:79]
	s_add_i32 s4, s76, 1
	s_cmp_lg_u32 s76, 2
	s_cselect_b32 s76, s4, 0
	s_add_i32 s4, s74, 1
	s_cmp_lg_u32 s74, 2
	s_cselect_b32 s74, s4, 0
	s_add_u32 s22, s22, 0x20000
	v_mfma_f32_32x32x16_bf16 v[48:63], v[140:143], v[154:157], v[48:63]
	s_addc_u32 s23, s23, 0
	s_add_i32 s86, s86, 1
	s_cmp_eq_u32 s22, 0x800000
	s_waitcnt lgkmcnt(0)
	v_mfma_f32_32x32x16_bf16 v[32:47], v[140:143], v[192:195], v[32:47]
	v_mfma_f32_32x32x16_bf16 v[16:31], v[140:143], v[196:199], v[16:31]
	s_cbranch_scc1 .LBB0_521
	v_mov_b32_e32 v232, v144
	s_cmp_eq_u32 s22, 0x7e0000
	s_mov_b64 s[4:5], -1
	s_cbranch_scc1 .LBB0_510

.LBB0_910:
	v_fmamk_f32 v144, v144, 0x3e0293ee, v237
	v_fmamk_f32 v145, v145, 0x3e0293ee, v237
	v_fmamk_f32 v146, v146, 0x3e0293ee, v237
	v_fmamk_f32 v147, v147, 0x3e0293ee, v237
	v_fmamk_f32 v148, v148, 0x3e0293ee, v237
	v_fmamk_f32 v149, v149, 0x3e0293ee, v237
	v_fmamk_f32 v150, v150, 0x3e0293ee, v237
	v_fmamk_f32 v151, v151, 0x3e0293ee, v237
	v_fmamk_f32 v152, v152, 0x3e0293ee, v237
	v_fmamk_f32 v153, v153, 0x3e0293ee, v237
	v_fmamk_f32 v154, v154, 0x3e0293ee, v237
	v_fmamk_f32 v155, v155, 0x3e0293ee, v237
	v_fmamk_f32 v156, v156, 0x3e0293ee, v237
	v_fmamk_f32 v157, v157, 0x3e0293ee, v237
	v_fmamk_f32 v158, v158, 0x3e0293ee, v237
	v_fmamk_f32 v159, v159, 0x3e0293ee, v237
	v_fmamk_f32 v128, v128, 0x3e0293ee, v237
	v_fmamk_f32 v129, v129, 0x3e0293ee, v237
	v_fmamk_f32 v130, v130, 0x3e0293ee, v237
	v_fmamk_f32 v131, v131, 0x3e0293ee, v237
	v_fmamk_f32 v132, v132, 0x3e0293ee, v237
	v_fmamk_f32 v133, v133, 0x3e0293ee, v237
	v_fmamk_f32 v134, v134, 0x3e0293ee, v237
	v_fmamk_f32 v135, v135, 0x3e0293ee, v237
	v_fmamk_f32 v136, v136, 0x3e0293ee, v237
	v_fmamk_f32 v137, v137, 0x3e0293ee, v237
	v_fmamk_f32 v138, v138, 0x3e0293ee, v237
	v_fmamk_f32 v139, v139, 0x3e0293ee, v237
	v_fmamk_f32 v140, v140, 0x3e0293ee, v237
	v_fmamk_f32 v141, v141, 0x3e0293ee, v237
	v_fmamk_f32 v142, v142, 0x3e0293ee, v237
	v_fmamk_f32 v192, v143, 0x3e0293ee, v237
	v_exp_f32_e32 v143, v144
	v_exp_f32_e32 v145, v145
	v_exp_f32_e32 v146, v146
	v_exp_f32_e32 v147, v147
	v_exp_f32_e32 v148, v148
	v_exp_f32_e32 v193, v128
	v_exp_f32_e32 v149, v149
	v_add_f32_e32 v128, v145, v143
	v_exp_f32_e32 v150, v150
	v_add_f32_e32 v128, v146, v128
	v_exp_f32_e32 v151, v151
	v_add_f32_e32 v128, v147, v128
	v_exp_f32_e32 v152, v152
	v_add_f32_e32 v128, v148, v128
	v_exp_f32_e32 v153, v153
	v_add_f32_e32 v128, v149, v128
	v_exp_f32_e32 v154, v154
	v_add_f32_e32 v128, v150, v128
	v_exp_f32_e32 v155, v155
	v_add_f32_e32 v128, v151, v128
	v_exp_f32_e32 v156, v156
	v_add_f32_e32 v128, v152, v128
	v_exp_f32_e32 v157, v157
	v_add_f32_e32 v128, v153, v128
	v_exp_f32_e32 v158, v158
	v_add_f32_e32 v128, v154, v128
	v_exp_f32_e32 v159, v159
	v_add_f32_e32 v128, v155, v128
	v_add_f32_e32 v128, v156, v128
	v_exp_f32_e32 v194, v129
	v_add_f32_e32 v128, v157, v128
	v_exp_f32_e32 v195, v130
	v_add_f32_e32 v128, v158, v128
	v_exp_f32_e32 v196, v131
	v_add_f32_e32 v128, v159, v128
	v_exp_f32_e32 v197, v132
	v_add_f32_e32 v128, v193, v128
	v_exp_f32_e32 v198, v133
	v_add_f32_e32 v128, v194, v128
	v_exp_f32_e32 v199, v134
	v_add_f32_e32 v128, v195, v128
	v_exp_f32_e32 v135, v135
	v_add_f32_e32 v128, v196, v128
	v_exp_f32_e32 v200, v136
	v_add_f32_e32 v128, v197, v128
	v_exp_f32_e32 v201, v137
	v_add_f32_e32 v128, v198, v128
	v_exp_f32_e32 v202, v138
	v_add_f32_e32 v128, v199, v128
	v_exp_f32_e32 v203, v139
	v_add_f32_e32 v128, v135, v128
	v_exp_f32_e32 v204, v140
	v_add_f32_e32 v128, v200, v128
	v_exp_f32_e32 v205, v141
	v_add_f32_e32 v128, v201, v128
	v_exp_f32_e32 v206, v142
	v_add_f32_e32 v128, v202, v128
	v_exp_f32_e32 v192, v192
	v_add_f32_e32 v128, v203, v128
	v_add_f32_e32 v128, v204, v128
	v_add_f32_e32 v128, v205, v128
	v_add_f32_e32 v128, v206, v128
	v_add_f32_e32 v128, v192, v128
	v_add_f32_e32 v144, v232, v128
	v_cvt_pk_bf16_f32 v128, v143, v145
	v_cvt_pk_bf16_f32 v129, v146, v147
	v_cvt_pk_bf16_f32 v130, v148, v149
	v_cvt_pk_bf16_f32 v131, v150, v151
	v_cvt_pk_bf16_f32 v136, v152, v153
	v_cvt_pk_bf16_f32 v137, v154, v155
	v_cvt_pk_bf16_f32 v138, v156, v157
	v_cvt_pk_bf16_f32 v139, v158, v159
	v_cvt_pk_bf16_f32 v132, v193, v194
	v_cvt_pk_bf16_f32 v133, v195, v196
	v_cvt_pk_bf16_f32 v134, v197, v198
	v_cvt_pk_bf16_f32 v135, v199, v135
	v_cvt_pk_bf16_f32 v140, v200, v201
	v_cvt_pk_bf16_f32 v141, v202, v203
	v_cvt_pk_bf16_f32 v142, v204, v205
	v_cvt_pk_bf16_f32 v143, v206, v192
	v_lshl_add_u32 v145, s80, 15, v230
	ds_read_b64_tr_b16 v[146:147], v145 offset:0
	ds_read_b64_tr_b16 v[148:149], v145 offset:4096
	ds_read_b64_tr_b16 v[150:151], v145 offset:512
	ds_read_b64_tr_b16 v[152:153], v145 offset:4608
	ds_read_b64_tr_b16 v[154:155], v145 offset:1024
	ds_read_b64_tr_b16 v[156:157], v145 offset:5120
	ds_read_b64_tr_b16 v[192:193], v145 offset:1536
	ds_read_b64_tr_b16 v[194:195], v145 offset:5632
	ds_read_b64_tr_b16 v[196:197], v145 offset:2048
	ds_read_b64_tr_b16 v[198:199], v145 offset:6144
	ds_read_b64_tr_b16 v[200:201], v145 offset:2560
	ds_read_b64_tr_b16 v[202:203], v145 offset:6656
	ds_read_b64_tr_b16 v[204:205], v145 offset:3072
	ds_read_b64_tr_b16 v[206:207], v145 offset:7168
	ds_read_b64_tr_b16 v[232:233], v145 offset:3584
	ds_read_b64_tr_b16 v[234:235], v145 offset:7680
	s_waitcnt lgkmcnt(12)
	s_nop 0
	v_mfma_f32_32x32x16_bf16 v[0:15], v[128:131], v[146:149], v[0:15]
	ds_read_b64_tr_b16 v[240:241], v145 offset:8192
	ds_read_b64_tr_b16 v[242:243], v145 offset:12288
	v_mfma_f32_32x32x16_bf16 v[112:127], v[128:131], v[150:153], v[112:127]
	ds_read_b64_tr_b16 v[146:147], v145 offset:8704
	ds_read_b64_tr_b16 v[148:149], v145 offset:12800
	s_waitcnt lgkmcnt(12)
	v_mfma_f32_32x32x16_bf16 v[96:111], v[128:131], v[154:157], v[96:111]
	ds_read_b64_tr_b16 v[150:151], v145 offset:9216
	ds_read_b64_tr_b16 v[152:153], v145 offset:13312
	v_mfma_f32_32x32x16_bf16 v[80:95], v[128:131], v[192:195], v[80:95]
	ds_read_b64_tr_b16 v[154:155], v145 offset:9728
	ds_read_b64_tr_b16 v[156:157], v145 offset:13824
	s_waitcnt lgkmcnt(12)
	v_mfma_f32_32x32x16_bf16 v[64:79], v[128:131], v[196:199], v[64:79]
	ds_read_b64_tr_b16 v[192:193], v145 offset:10240
	ds_read_b64_tr_b16 v[194:195], v145 offset:14336
	v_mfma_f32_32x32x16_bf16 v[48:63], v[128:131], v[200:203], v[48:63]
	ds_read_b64_tr_b16 v[196:197], v145 offset:10752
	ds_read_b64_tr_b16 v[198:199], v145 offset:14848
	s_waitcnt lgkmcnt(12)
	v_mfma_f32_32x32x16_bf16 v[32:47], v[128:131], v[204:207], v[32:47]
	ds_read_b64_tr_b16 v[200:201], v145 offset:11264
	ds_read_b64_tr_b16 v[202:203], v145 offset:15360
	v_mfma_f32_32x32x16_bf16 v[16:31], v[128:131], v[232:235], v[16:31]
	ds_read_b64_tr_b16 v[204:205], v145 offset:11776
	ds_read_b64_tr_b16 v[206:207], v145 offset:15872
	s_waitcnt lgkmcnt(12)
	v_mfma_f32_32x32x16_bf16 v[0:15], v[136:139], v[240:243], v[0:15]
	ds_read_b64_tr_b16 v[232:233], v145 offset:16384
	ds_read_b64_tr_b16 v[234:235], v145 offset:20480
	v_mfma_f32_32x32x16_bf16 v[112:127], v[136:139], v[146:149], v[112:127]
	ds_read_b64_tr_b16 v[240:241], v145 offset:16896
	ds_read_b64_tr_b16 v[242:243], v145 offset:20992
	s_waitcnt lgkmcnt(12)
	v_mfma_f32_32x32x16_bf16 v[96:111], v[136:139], v[150:153], v[96:111]
	ds_read_b64_tr_b16 v[146:147], v145 offset:17408
	ds_read_b64_tr_b16 v[148:149], v145 offset:21504
	v_mfma_f32_32x32x16_bf16 v[80:95], v[136:139], v[154:157], v[80:95]
	ds_read_b64_tr_b16 v[150:151], v145 offset:17920
	ds_read_b64_tr_b16 v[152:153], v145 offset:22016
	s_waitcnt lgkmcnt(12)
	v_mfma_f32_32x32x16_bf16 v[64:79], v[136:139], v[192:195], v[64:79]
	ds_read_b64_tr_b16 v[154:155], v145 offset:18432
	ds_read_b64_tr_b16 v[156:157], v145 offset:22528
	v_mfma_f32_32x32x16_bf16 v[48:63], v[136:139], v[196:199], v[48:63]
	ds_read_b64_tr_b16 v[192:193], v145 offset:18944
	ds_read_b64_tr_b16 v[194:195], v145 offset:23040
	s_waitcnt lgkmcnt(12)
	v_mfma_f32_32x32x16_bf16 v[32:47], v[136:139], v[200:203], v[32:47]
	ds_read_b64_tr_b16 v[196:197], v145 offset:19456
	ds_read_b64_tr_b16 v[198:199], v145 offset:23552
	v_mfma_f32_32x32x16_bf16 v[16:31], v[136:139], v[204:207], v[16:31]
	ds_read_b64_tr_b16 v[200:201], v145 offset:19968
	ds_read_b64_tr_b16 v[202:203], v145 offset:24064
	s_waitcnt lgkmcnt(12)
	v_mfma_f32_32x32x16_bf16 v[0:15], v[132:135], v[232:235], v[0:15]
	ds_read_b64_tr_b16 v[204:205], v145 offset:24576
	ds_read_b64_tr_b16 v[206:207], v145 offset:28672
	v_mfma_f32_32x32x16_bf16 v[112:127], v[132:135], v[240:243], v[112:127]
	ds_read_b64_tr_b16 v[232:233], v145 offset:25088
	ds_read_b64_tr_b16 v[234:235], v145 offset:29184
	s_waitcnt lgkmcnt(12)
	v_mfma_f32_32x32x16_bf16 v[96:111], v[132:135], v[146:149], v[96:111]
	ds_read_b64_tr_b16 v[240:241], v145 offset:25600
	ds_read_b64_tr_b16 v[242:243], v145 offset:29696
	v_mfma_f32_32x32x16_bf16 v[80:95], v[132:135], v[150:153], v[80:95]
	ds_read_b64_tr_b16 v[146:147], v145 offset:26112
	ds_read_b64_tr_b16 v[148:149], v145 offset:30208
	s_waitcnt lgkmcnt(12)
	v_mfma_f32_32x32x16_bf16 v[64:79], v[132:135], v[154:157], v[64:79]
	ds_read_b64_tr_b16 v[150:151], v145 offset:26624
	ds_read_b64_tr_b16 v[152:153], v145 offset:30720
	v_mfma_f32_32x32x16_bf16 v[48:63], v[132:135], v[192:195], v[48:63]
	ds_read_b64_tr_b16 v[154:155], v145 offset:27136
	ds_read_b64_tr_b16 v[156:157], v145 offset:31232
	s_waitcnt lgkmcnt(12)
	v_mfma_f32_32x32x16_bf16 v[32:47], v[132:135], v[196:199], v[32:47]
	ds_read_b64_tr_b16 v[192:193], v145 offset:27648
	ds_read_b64_tr_b16 v[194:195], v145 offset:31744
	v_mfma_f32_32x32x16_bf16 v[16:31], v[132:135], v[200:203], v[16:31]
	ds_read_b64_tr_b16 v[196:197], v145 offset:28160
	ds_read_b64_tr_b16 v[198:199], v145 offset:32256
	s_waitcnt lgkmcnt(12)
	v_mfma_f32_32x32x16_bf16 v[0:15], v[140:143], v[204:207], v[0:15]
	v_mfma_f32_32x32x16_bf16 v[112:127], v[140:143], v[232:235], v[112:127]
	s_waitcnt lgkmcnt(8)
	v_mfma_f32_32x32x16_bf16 v[96:111], v[140:143], v[240:243], v[96:111]
	v_mfma_f32_32x32x16_bf16 v[80:95], v[140:143], v[146:149], v[80:95]
	s_waitcnt lgkmcnt(4)
	v_mfma_f32_32x32x16_bf16 v[64:79], v[140:143], v[150:153], v[64:79]
	s_add_i32 s4, s80, 1
	s_cmp_lg_u32 s80, 2
	s_cselect_b32 s80, s4, 0
	s_add_i32 s4, s78, 1
	s_cmp_lg_u32 s78, 2
	s_cselect_b32 s78, s4, 0
	s_add_u32 s22, s22, 0x20000
	v_mfma_f32_32x32x16_bf16 v[48:63], v[140:143], v[154:157], v[48:63]
	s_addc_u32 s23, s23, 0
	s_add_i32 s86, s86, 1
	s_cmp_eq_u32 s22, 0x800000
	s_waitcnt lgkmcnt(0)
	v_mfma_f32_32x32x16_bf16 v[32:47], v[140:143], v[192:195], v[32:47]
	v_mfma_f32_32x32x16_bf16 v[16:31], v[140:143], v[196:199], v[16:31]
	s_cbranch_scc1 .LBB0_914
	v_mov_b32_e32 v232, v144
	s_cmp_eq_u32 s22, 0x7e0000
	s_mov_b64 s[4:5], -1
	s_cbranch_scc1 .LBB0_903
